# score reductions: levels xor 1,2,4,8 done with DPP adds (quad_perm / row_half_mirror / row_mirror) instead of ds_bpermute round trips; only the xor-16 level still uses the LDS crossbar
# speedup vs baseline: 1.0180x; 1.0007x over previous
.LBB0_556:
	v_mov_b32_e32 v132, v208
	v_readlane_b32 s38, v254, 35
	v_and_b32_e32 v133, 31, v132
	v_lshlrev_b32_e32 v2, 3, v133
	v_readlane_b32 s39, v254, 36
	v_bfe_u32 v146, v132, 5, 1
	s_waitcnt vmcnt(0)
	v_or_b32_e32 v4, s3, v146
	s_waitcnt vmcnt(26)
	v_ashrrev_i32_e32 v5, 31, v4
	s_waitcnt vmcnt(0)
	v_lshlrev_b64 v[80:81], 9, v[4:5]
	v_lshl_add_u64 v[4:5], s[70:71], 0, v[80:81]
	global_load_dwordx2 v[138:139], v2, s[38:39]
	v_readlane_b32 s38, v254, 37
	v_readlane_b32 s39, v254, 38
	v_lshlrev_b64 v[4:5], 2, v[4:5]
	s_waitcnt vmcnt(0)
	v_lshlrev_b32_e32 v83, 16, v138
	s_nop 1
	global_load_dwordx2 v[134:135], v2, s[38:39]
	v_readlane_b32 s38, v253, 11
	v_readlane_b32 s39, v253, 12
	s_load_dwordx4 s[40:43], s[38:39], 0x10
	v_lshlrev_b32_e32 v2, 4, v133
	v_lshlrev_b32_e32 v82, 16, v139
	s_waitcnt lgkmcnt(0)
	v_lshl_add_u64 v[6:7], s[40:41], 0, v[4:5]
	v_lshl_add_u64 v[32:33], s[42:43], 0, v[4:5]
	v_lshl_add_u64 v[4:5], v[6:7], 0, v[2:3]
	v_add_co_u32_e32 v6, vcc, s91, v4
	s_movk_i32 s1, 0x6000
	s_nop 0
	v_addc_co_u32_e32 v7, vcc, 0, v5, vcc
	global_load_dwordx4 v[76:79], v[6:7], off offset:-4096 nt
	global_load_dwordx4 v[72:75], v[6:7], off nt
	v_add_co_u32_e32 v6, vcc, s90, v4
	v_lshl_add_u64 v[32:33], v[32:33], 0, v[2:3]
	s_nop 0
	v_addc_co_u32_e32 v7, vcc, 0, v5, vcc
	global_load_dwordx4 v[68:71], v[6:7], off offset:-4096 nt
	global_load_dwordx4 v[60:63], v[6:7], off nt
	v_add_co_u32_e32 v6, vcc, s1, v4
	s_movk_i32 s33, 0x6000
	s_nop 0
	v_addc_co_u32_e32 v7, vcc, 0, v5, vcc
	global_load_dwordx4 v[52:55], v[6:7], off offset:-4096 nt
	global_load_dwordx4 v[48:51], v[6:7], off nt
	v_add_co_u32_e32 v6, vcc, s92, v4
	v_and_b32_e32 v137, 0xffff0000, v138
	s_nop 0
	v_addc_co_u32_e32 v7, vcc, 0, v5, vcc
	global_load_dwordx4 v[40:43], v[6:7], off offset:-4096 nt
	global_load_dwordx4 v[36:39], v[6:7], off nt
	v_add_co_u32_e32 v6, vcc, s93, v4
	v_and_b32_e32 v136, 0xffff0000, v139
	s_nop 0
	v_addc_co_u32_e32 v7, vcc, 0, v5, vcc
	global_load_dwordx4 v[28:31], v[6:7], off offset:-4096 nt
	global_load_dwordx4 v[24:27], v[6:7], off nt
	v_add_co_u32_e32 v6, vcc, s6, v4
	s_nop 1
	v_addc_co_u32_e32 v7, vcc, 0, v5, vcc
	global_load_dwordx4 v[20:23], v[6:7], off offset:-4096 nt
	global_load_dwordx4 v[16:19], v[6:7], off nt
	v_add_co_u32_e32 v6, vcc, s95, v4
	s_nop 1
	v_addc_co_u32_e32 v7, vcc, 0, v5, vcc
	global_load_dwordx4 v[12:15], v[6:7], off offset:-4096 nt
	global_load_dwordx4 v[8:11], v[6:7], off nt
	v_add_co_u32_e32 v6, vcc, s52, v4
	s_nop 1
	v_addc_co_u32_e32 v7, vcc, 0, v5, vcc
	v_add_co_u32_e32 v34, vcc, s91, v32
	global_load_dwordx4 v[142:145], v[4:5], off nt
	s_nop 0
	global_load_dwordx4 v[4:7], v[6:7], off nt
	v_addc_co_u32_e32 v35, vcc, 0, v33, vcc
	global_load_dwordx4 v[124:127], v[34:35], off offset:-4096 nt
	global_load_dwordx4 v[116:119], v[34:35], off nt
	v_add_co_u32_e32 v34, vcc, s90, v32
	s_nop 1
	v_addc_co_u32_e32 v35, vcc, 0, v33, vcc
	global_load_dwordx4 v[120:123], v[34:35], off offset:-4096 nt
	global_load_dwordx4 v[108:111], v[34:35], off nt
	v_add_co_u32_e32 v34, vcc, s1, v32
	s_nop 1
	v_addc_co_u32_e32 v35, vcc, 0, v33, vcc
	global_load_dwordx4 v[112:115], v[34:35], off offset:-4096 nt
	global_load_dwordx4 v[100:103], v[34:35], off nt
	v_add_co_u32_e32 v34, vcc, s92, v32
	s_nop 1
	v_addc_co_u32_e32 v35, vcc, 0, v33, vcc
	global_load_dwordx4 v[104:107], v[34:35], off offset:-4096 nt
	global_load_dwordx4 v[92:95], v[34:35], off nt
	v_add_co_u32_e32 v34, vcc, s93, v32
	s_nop 1
	v_addc_co_u32_e32 v35, vcc, 0, v33, vcc
	global_load_dwordx4 v[96:99], v[34:35], off offset:-4096 nt
	global_load_dwordx4 v[84:87], v[34:35], off nt
	v_add_co_u32_e32 v34, vcc, s6, v32
	s_nop 1
	v_addc_co_u32_e32 v35, vcc, 0, v33, vcc
	global_load_dwordx4 v[88:91], v[34:35], off offset:-4096 nt
	global_load_dwordx4 v[64:67], v[34:35], off nt
	v_add_co_u32_e32 v34, vcc, s95, v32
	s_nop 1
	v_addc_co_u32_e32 v35, vcc, 0, v33, vcc
	global_load_dwordx4 v[56:59], v[34:35], off offset:-4096 nt
	global_load_dwordx4 v[44:47], v[34:35], off nt
	v_add_co_u32_e32 v34, vcc, s52, v32
	s_nop 1
	v_addc_co_u32_e32 v35, vcc, 0, v33, vcc
	global_load_dwordx4 v[128:131], v[32:33], off nt
	s_nop 0
	global_load_dwordx4 v[32:35], v[34:35], off nt
	v_xor_b32_e32 v138, 1, v231
	v_cmp_lt_i32_e32 vcc, v138, v235
	s_waitcnt vmcnt(17)
	v_mul_f32_e32 v139, v145, v136
	v_fmac_f32_e32 v139, v144, v82
	v_cndmask_b32_e32 v138, v231, v138, vcc
	v_lshlrev_b32_e32 v140, 2, v138
	v_mul_f32_e32 v138, v143, v137
	v_fmac_f32_e32 v138, v142, v83
	v_add_f32_e32 v138, v138, v139
	v_mul_f32_e32 v77, v77, v137
	v_fmac_f32_e32 v77, v76, v83
	v_mul_f32_e32 v76, v79, v136
	v_fmac_f32_e32 v76, v78, v82
	v_add_f32_e32 v76, v77, v76
	v_mul_f32_e32 v73, v73, v137
	v_fmac_f32_e32 v73, v72, v83
	v_mul_f32_e32 v72, v75, v136
	v_fmac_f32_e32 v72, v74, v82
	v_add_f32_e32 v72, v73, v72
	v_mul_f32_e32 v69, v69, v137
	v_fmac_f32_e32 v69, v68, v83
	v_mul_f32_e32 v68, v71, v136
	v_fmac_f32_e32 v68, v70, v82
	v_add_f32_e32 v68, v69, v68
	v_mul_f32_e32 v61, v61, v137
	v_fmac_f32_e32 v61, v60, v83
	v_mul_f32_e32 v60, v63, v136
	v_fmac_f32_e32 v60, v62, v82
	v_add_f32_e32 v60, v61, v60
	v_mul_f32_e32 v53, v53, v137
	v_fmac_f32_e32 v53, v52, v83
	v_mul_f32_e32 v52, v55, v136
	v_fmac_f32_e32 v52, v54, v82
	v_add_f32_e32 v52, v53, v52
	v_mul_f32_e32 v49, v49, v137
	v_fmac_f32_e32 v49, v48, v83
	v_mul_f32_e32 v48, v51, v136
	v_fmac_f32_e32 v48, v50, v82
	v_add_f32_e32 v48, v49, v48
	v_mul_f32_e32 v41, v41, v137
	v_fmac_f32_e32 v41, v40, v83
	v_mul_f32_e32 v40, v43, v136
	v_fmac_f32_e32 v40, v42, v82
	v_add_f32_e32 v40, v41, v40
	v_mul_f32_e32 v37, v37, v137
	v_fmac_f32_e32 v37, v36, v83
	v_mul_f32_e32 v36, v39, v136
	v_fmac_f32_e32 v36, v38, v82
	v_add_f32_e32 v36, v37, v36
	v_mul_f32_e32 v29, v29, v137
	v_fmac_f32_e32 v29, v28, v83
	v_mul_f32_e32 v28, v31, v136
	v_fmac_f32_e32 v28, v30, v82
	v_add_f32_e32 v28, v29, v28
	v_mul_f32_e32 v25, v25, v137
	v_fmac_f32_e32 v25, v24, v83
	v_mul_f32_e32 v24, v27, v136
	v_fmac_f32_e32 v24, v26, v82
	v_add_f32_e32 v24, v25, v24
	v_mul_f32_e32 v21, v21, v137
	v_fmac_f32_e32 v21, v20, v83
	v_mul_f32_e32 v20, v23, v136
	v_fmac_f32_e32 v20, v22, v82
	v_add_f32_e32 v20, v21, v20
	v_mul_f32_e32 v17, v17, v137
	v_fmac_f32_e32 v17, v16, v83
	v_mul_f32_e32 v16, v19, v136
	v_fmac_f32_e32 v16, v18, v82
	v_add_f32_e32 v16, v17, v16
	v_mul_f32_e32 v13, v13, v137
	v_fmac_f32_e32 v13, v12, v83
	v_mul_f32_e32 v12, v15, v136
	v_fmac_f32_e32 v12, v14, v82
	v_add_f32_e32 v12, v13, v12
	v_mul_f32_e32 v9, v9, v137
	v_fmac_f32_e32 v9, v8, v83
	v_mul_f32_e32 v8, v11, v136
	v_fmac_f32_e32 v8, v10, v82
	v_add_f32_e32 v8, v9, v8
	s_waitcnt vmcnt(16)
	v_mul_f32_e32 v5, v5, v137
	v_fmac_f32_e32 v5, v4, v83
	v_mul_f32_e32 v4, v7, v136
	v_fmac_f32_e32 v4, v6, v82
	v_add_f32_e32 v4, v5, v4
	v_xor_b32_e32 v141, 2, v231
	v_cmp_lt_i32_e32 vcc, v141, v235
	s_nop 1
	v_xor_b32_e32 v142, 4, v231
	v_xor_b32_e32 v143, 8, v231
	v_cndmask_b32_e32 v141, v231, v141, vcc
	v_lshlrev_b32_e32 v141, 2, v141
	v_cmp_lt_i32_e32 vcc, v142, v235
	s_nop 1
	v_readlane_b32 s1, v254, 32
	v_cmp_eq_u32_e64 s[38:39], 0, v133
	s_nop 1
	v_cndmask_b32_e32 v142, v231, v142, vcc
	v_lshlrev_b32_e32 v142, 2, v142
	v_cmp_lt_i32_e32 vcc, v143, v235
	s_nop 1
	v_cndmask_b32_e32 v143, v231, v143, vcc
	v_lshlrev_b32_e32 v143, 2, v143
	v_cmp_lt_i32_e32 vcc, v234, v235
	s_nop 1
	v_cndmask_b32_e32 v144, v231, v234, vcc
	v_lshlrev_b32_e32 v144, 2, v144
	v_add_f32_dpp v138, v138, v138 quad_perm:[1,0,3,2] row_mask:0xf bank_mask:0xf
	v_add_f32_dpp v76, v76, v76 quad_perm:[1,0,3,2] row_mask:0xf bank_mask:0xf
	v_add_f32_dpp v72, v72, v72 quad_perm:[1,0,3,2] row_mask:0xf bank_mask:0xf
	v_add_f32_dpp v68, v68, v68 quad_perm:[1,0,3,2] row_mask:0xf bank_mask:0xf
	v_add_f32_dpp v60, v60, v60 quad_perm:[1,0,3,2] row_mask:0xf bank_mask:0xf
	v_add_f32_dpp v52, v52, v52 quad_perm:[1,0,3,2] row_mask:0xf bank_mask:0xf
	v_add_f32_dpp v48, v48, v48 quad_perm:[1,0,3,2] row_mask:0xf bank_mask:0xf
	v_add_f32_dpp v40, v40, v40 quad_perm:[1,0,3,2] row_mask:0xf bank_mask:0xf
	v_add_f32_dpp v36, v36, v36 quad_perm:[1,0,3,2] row_mask:0xf bank_mask:0xf
	v_add_f32_dpp v28, v28, v28 quad_perm:[1,0,3,2] row_mask:0xf bank_mask:0xf
	v_add_f32_dpp v24, v24, v24 quad_perm:[1,0,3,2] row_mask:0xf bank_mask:0xf
	v_add_f32_dpp v20, v20, v20 quad_perm:[1,0,3,2] row_mask:0xf bank_mask:0xf
	v_add_f32_dpp v16, v16, v16 quad_perm:[1,0,3,2] row_mask:0xf bank_mask:0xf
	v_add_f32_dpp v12, v12, v12 quad_perm:[1,0,3,2] row_mask:0xf bank_mask:0xf
	v_add_f32_dpp v8, v8, v8 quad_perm:[1,0,3,2] row_mask:0xf bank_mask:0xf
	v_add_f32_dpp v4, v4, v4 quad_perm:[1,0,3,2] row_mask:0xf bank_mask:0xf
	v_add_f32_dpp v138, v138, v138 quad_perm:[2,3,0,1] row_mask:0xf bank_mask:0xf
	v_add_f32_dpp v76, v76, v76 quad_perm:[2,3,0,1] row_mask:0xf bank_mask:0xf
	v_add_f32_dpp v72, v72, v72 quad_perm:[2,3,0,1] row_mask:0xf bank_mask:0xf
	v_add_f32_dpp v68, v68, v68 quad_perm:[2,3,0,1] row_mask:0xf bank_mask:0xf
	v_add_f32_dpp v60, v60, v60 quad_perm:[2,3,0,1] row_mask:0xf bank_mask:0xf
	v_add_f32_dpp v52, v52, v52 quad_perm:[2,3,0,1] row_mask:0xf bank_mask:0xf
	v_add_f32_dpp v48, v48, v48 quad_perm:[2,3,0,1] row_mask:0xf bank_mask:0xf
	v_add_f32_dpp v40, v40, v40 quad_perm:[2,3,0,1] row_mask:0xf bank_mask:0xf
	v_add_f32_dpp v36, v36, v36 quad_perm:[2,3,0,1] row_mask:0xf bank_mask:0xf
	v_add_f32_dpp v28, v28, v28 quad_perm:[2,3,0,1] row_mask:0xf bank_mask:0xf
	v_add_f32_dpp v24, v24, v24 quad_perm:[2,3,0,1] row_mask:0xf bank_mask:0xf
	v_add_f32_dpp v20, v20, v20 quad_perm:[2,3,0,1] row_mask:0xf bank_mask:0xf
	v_add_f32_dpp v16, v16, v16 quad_perm:[2,3,0,1] row_mask:0xf bank_mask:0xf
	v_add_f32_dpp v12, v12, v12 quad_perm:[2,3,0,1] row_mask:0xf bank_mask:0xf
	v_add_f32_dpp v8, v8, v8 quad_perm:[2,3,0,1] row_mask:0xf bank_mask:0xf
	v_add_f32_dpp v4, v4, v4 quad_perm:[2,3,0,1] row_mask:0xf bank_mask:0xf
	v_add_f32_dpp v138, v138, v138 row_half_mirror row_mask:0xf bank_mask:0xf
	v_add_f32_dpp v76, v76, v76 row_half_mirror row_mask:0xf bank_mask:0xf
	v_add_f32_dpp v72, v72, v72 row_half_mirror row_mask:0xf bank_mask:0xf
	v_add_f32_dpp v68, v68, v68 row_half_mirror row_mask:0xf bank_mask:0xf
	v_add_f32_dpp v60, v60, v60 row_half_mirror row_mask:0xf bank_mask:0xf
	v_add_f32_dpp v52, v52, v52 row_half_mirror row_mask:0xf bank_mask:0xf
	v_add_f32_dpp v48, v48, v48 row_half_mirror row_mask:0xf bank_mask:0xf
	v_add_f32_dpp v40, v40, v40 row_half_mirror row_mask:0xf bank_mask:0xf
	v_add_f32_dpp v36, v36, v36 row_half_mirror row_mask:0xf bank_mask:0xf
	v_add_f32_dpp v28, v28, v28 row_half_mirror row_mask:0xf bank_mask:0xf
	v_add_f32_dpp v24, v24, v24 row_half_mirror row_mask:0xf bank_mask:0xf
	v_add_f32_dpp v20, v20, v20 row_half_mirror row_mask:0xf bank_mask:0xf
	v_add_f32_dpp v16, v16, v16 row_half_mirror row_mask:0xf bank_mask:0xf
	v_add_f32_dpp v12, v12, v12 row_half_mirror row_mask:0xf bank_mask:0xf
	v_add_f32_dpp v8, v8, v8 row_half_mirror row_mask:0xf bank_mask:0xf
	v_add_f32_dpp v4, v4, v4 row_half_mirror row_mask:0xf bank_mask:0xf
	v_add_f32_dpp v138, v138, v138 row_mirror row_mask:0xf bank_mask:0xf
	v_add_f32_dpp v76, v76, v76 row_mirror row_mask:0xf bank_mask:0xf
	v_add_f32_dpp v72, v72, v72 row_mirror row_mask:0xf bank_mask:0xf
	v_add_f32_dpp v68, v68, v68 row_mirror row_mask:0xf bank_mask:0xf
	v_add_f32_dpp v60, v60, v60 row_mirror row_mask:0xf bank_mask:0xf
	v_add_f32_dpp v52, v52, v52 row_mirror row_mask:0xf bank_mask:0xf
	v_add_f32_dpp v48, v48, v48 row_mirror row_mask:0xf bank_mask:0xf
	v_add_f32_dpp v40, v40, v40 row_mirror row_mask:0xf bank_mask:0xf
	v_add_f32_dpp v36, v36, v36 row_mirror row_mask:0xf bank_mask:0xf
	v_add_f32_dpp v28, v28, v28 row_mirror row_mask:0xf bank_mask:0xf
	v_add_f32_dpp v24, v24, v24 row_mirror row_mask:0xf bank_mask:0xf
	v_add_f32_dpp v20, v20, v20 row_mirror row_mask:0xf bank_mask:0xf
	v_add_f32_dpp v16, v16, v16 row_mirror row_mask:0xf bank_mask:0xf
	v_add_f32_dpp v12, v12, v12 row_mirror row_mask:0xf bank_mask:0xf
	v_add_f32_dpp v8, v8, v8 row_mirror row_mask:0xf bank_mask:0xf
	v_add_f32_dpp v4, v4, v4 row_mirror row_mask:0xf bank_mask:0xf
	ds_bpermute_b32 v145, v144, v138
	ds_bpermute_b32 v77, v144, v76
	ds_bpermute_b32 v73, v144, v72
	ds_bpermute_b32 v69, v144, v68
	ds_bpermute_b32 v61, v144, v60
	ds_bpermute_b32 v53, v144, v52
	ds_bpermute_b32 v49, v144, v48
	ds_bpermute_b32 v41, v144, v40
	ds_bpermute_b32 v37, v144, v36
	ds_bpermute_b32 v29, v144, v28
	ds_bpermute_b32 v25, v144, v24
	ds_bpermute_b32 v21, v144, v20
	ds_bpermute_b32 v17, v144, v16
	ds_bpermute_b32 v13, v144, v12
	ds_bpermute_b32 v9, v144, v8
	ds_bpermute_b32 v5, v144, v4
	s_waitcnt lgkmcnt(0)
	v_add_f32_e32 v138, v138, v145
	v_add_f32_e32 v76, v76, v77
	v_add_f32_e32 v72, v72, v73
	v_add_f32_e32 v68, v68, v69
	v_add_f32_e32 v60, v60, v61
	v_add_f32_e32 v52, v52, v53
	v_add_f32_e32 v48, v48, v49
	v_add_f32_e32 v40, v40, v41
	v_add_f32_e32 v36, v36, v37
	v_add_f32_e32 v28, v28, v29
	v_add_f32_e32 v24, v24, v25
	v_add_f32_e32 v20, v20, v21
	v_add_f32_e32 v16, v16, v17
	v_add_f32_e32 v12, v12, v13
	v_add_f32_e32 v8, v8, v9
	v_add_f32_e32 v4, v4, v5
	v_lshl_add_u32 v139, v146, 2, s1
	s_and_saveexec_b64 s[44:45], s[38:39]
	s_cbranch_execz .Lmy_sc_aa
	ds_write_b32 v139, v138
	ds_write_b32 v139, v76 offset:8
	ds_write_b32 v139, v72 offset:16
	ds_write_b32 v139, v68 offset:24
	ds_write_b32 v139, v60 offset:32
	ds_write_b32 v139, v52 offset:40
	ds_write_b32 v139, v48 offset:48
	ds_write_b32 v139, v40 offset:56
	ds_write_b32 v139, v36 offset:64
	ds_write_b32 v139, v28 offset:72
	ds_write_b32 v139, v24 offset:80
	ds_write_b32 v139, v20 offset:88
	ds_write_b32 v139, v16 offset:96
	ds_write_b32 v139, v12 offset:104
	ds_write_b32 v139, v8 offset:112
	ds_write_b32 v139, v4 offset:120

.LBB0_592:
	s_or_b64 exec, exec, s[44:45]
	v_and_b32_e32 v147, 0xffff0000, v134
	v_lshlrev_b32_e32 v137, 16, v134
	v_and_b32_e32 v134, 0xffff0000, v135
	s_waitcnt vmcnt(31)
	v_mul_f32_e32 v81, v81, v147
	v_lshlrev_b32_e32 v136, 16, v135
	v_fmac_f32_e32 v81, v80, v137
	v_mul_f32_e32 v80, v83, v134
	v_fmac_f32_e32 v80, v82, v136
	v_add_f32_e32 v80, v81, v80
	s_waitcnt vmcnt(30)
	v_mul_f32_e32 v77, v77, v147
	v_fmac_f32_e32 v77, v76, v137
	v_mul_f32_e32 v76, v79, v134
	v_fmac_f32_e32 v76, v78, v136
	v_add_f32_e32 v76, v77, v76
	s_waitcnt vmcnt(29)
	v_mul_f32_e32 v73, v73, v147
	v_fmac_f32_e32 v73, v72, v137
	v_mul_f32_e32 v72, v75, v134
	v_fmac_f32_e32 v72, v74, v136
	v_add_f32_e32 v72, v73, v72
	s_waitcnt vmcnt(28)
	v_mul_f32_e32 v69, v69, v147
	v_fmac_f32_e32 v69, v68, v137
	v_mul_f32_e32 v68, v71, v134
	v_fmac_f32_e32 v68, v70, v136
	v_add_f32_e32 v68, v69, v68
	s_waitcnt vmcnt(27)
	v_mul_f32_e32 v61, v61, v147
	v_fmac_f32_e32 v61, v60, v137
	v_mul_f32_e32 v60, v63, v134
	v_fmac_f32_e32 v60, v62, v136
	v_add_f32_e32 v60, v61, v60
	s_waitcnt vmcnt(26)
	v_mul_f32_e32 v53, v53, v147
	v_fmac_f32_e32 v53, v52, v137
	v_mul_f32_e32 v52, v55, v134
	v_fmac_f32_e32 v52, v54, v136
	v_add_f32_e32 v52, v53, v52
	s_waitcnt vmcnt(25)
	v_mul_f32_e32 v49, v49, v147
	v_fmac_f32_e32 v49, v48, v137
	v_mul_f32_e32 v48, v51, v134
	v_fmac_f32_e32 v48, v50, v136
	v_add_f32_e32 v48, v49, v48
	s_waitcnt vmcnt(24)
	v_mul_f32_e32 v41, v41, v147
	v_fmac_f32_e32 v41, v40, v137
	v_mul_f32_e32 v40, v43, v134
	v_fmac_f32_e32 v40, v42, v136
	v_add_f32_e32 v40, v41, v40
	s_waitcnt vmcnt(23)
	v_mul_f32_e32 v37, v37, v147
	v_fmac_f32_e32 v37, v36, v137
	v_mul_f32_e32 v36, v39, v134
	v_fmac_f32_e32 v36, v38, v136
	v_add_f32_e32 v36, v37, v36
	s_waitcnt vmcnt(22)
	v_mul_f32_e32 v29, v29, v147
	v_fmac_f32_e32 v29, v28, v137
	v_mul_f32_e32 v28, v31, v134
	v_fmac_f32_e32 v28, v30, v136
	v_add_f32_e32 v28, v29, v28
	s_waitcnt vmcnt(21)
	v_mul_f32_e32 v25, v25, v147
	v_fmac_f32_e32 v25, v24, v137
	v_mul_f32_e32 v24, v27, v134
	v_fmac_f32_e32 v24, v26, v136
	v_add_f32_e32 v24, v25, v24
	s_waitcnt vmcnt(20)
	v_mul_f32_e32 v21, v21, v147
	v_fmac_f32_e32 v21, v20, v137
	v_mul_f32_e32 v20, v23, v134
	v_fmac_f32_e32 v20, v22, v136
	v_add_f32_e32 v20, v21, v20
	s_waitcnt vmcnt(19)
	v_mul_f32_e32 v17, v17, v147
	v_fmac_f32_e32 v17, v16, v137
	v_mul_f32_e32 v16, v19, v134
	v_fmac_f32_e32 v16, v18, v136
	v_add_f32_e32 v16, v17, v16
	s_waitcnt vmcnt(18)
	v_mul_f32_e32 v13, v13, v147
	v_fmac_f32_e32 v13, v12, v137
	v_mul_f32_e32 v12, v15, v134
	v_fmac_f32_e32 v12, v14, v136
	v_add_f32_e32 v12, v13, v12
	s_waitcnt vmcnt(17)
	v_mul_f32_e32 v9, v9, v147
	v_fmac_f32_e32 v9, v8, v137
	v_mul_f32_e32 v8, v11, v134
	v_fmac_f32_e32 v8, v10, v136
	v_add_f32_e32 v8, v9, v8
	s_waitcnt vmcnt(16)
	v_mul_f32_e32 v5, v5, v147
	v_fmac_f32_e32 v5, v4, v137
	v_mul_f32_e32 v4, v7, v134
	v_fmac_f32_e32 v4, v6, v136
	v_add_f32_e32 v4, v5, v4
	v_add_f32_dpp v80, v80, v80 quad_perm:[1,0,3,2] row_mask:0xf bank_mask:0xf
	v_add_f32_dpp v76, v76, v76 quad_perm:[1,0,3,2] row_mask:0xf bank_mask:0xf
	v_add_f32_dpp v72, v72, v72 quad_perm:[1,0,3,2] row_mask:0xf bank_mask:0xf
	v_add_f32_dpp v68, v68, v68 quad_perm:[1,0,3,2] row_mask:0xf bank_mask:0xf
	v_add_f32_dpp v60, v60, v60 quad_perm:[1,0,3,2] row_mask:0xf bank_mask:0xf
	v_add_f32_dpp v52, v52, v52 quad_perm:[1,0,3,2] row_mask:0xf bank_mask:0xf
	v_add_f32_dpp v48, v48, v48 quad_perm:[1,0,3,2] row_mask:0xf bank_mask:0xf
	v_add_f32_dpp v40, v40, v40 quad_perm:[1,0,3,2] row_mask:0xf bank_mask:0xf
	v_add_f32_dpp v36, v36, v36 quad_perm:[1,0,3,2] row_mask:0xf bank_mask:0xf
	v_add_f32_dpp v28, v28, v28 quad_perm:[1,0,3,2] row_mask:0xf bank_mask:0xf
	v_add_f32_dpp v24, v24, v24 quad_perm:[1,0,3,2] row_mask:0xf bank_mask:0xf
	v_add_f32_dpp v20, v20, v20 quad_perm:[1,0,3,2] row_mask:0xf bank_mask:0xf
	v_add_f32_dpp v16, v16, v16 quad_perm:[1,0,3,2] row_mask:0xf bank_mask:0xf
	v_add_f32_dpp v12, v12, v12 quad_perm:[1,0,3,2] row_mask:0xf bank_mask:0xf
	v_add_f32_dpp v8, v8, v8 quad_perm:[1,0,3,2] row_mask:0xf bank_mask:0xf
	v_add_f32_dpp v4, v4, v4 quad_perm:[1,0,3,2] row_mask:0xf bank_mask:0xf
	v_add_f32_dpp v80, v80, v80 quad_perm:[2,3,0,1] row_mask:0xf bank_mask:0xf
	v_add_f32_dpp v76, v76, v76 quad_perm:[2,3,0,1] row_mask:0xf bank_mask:0xf
	v_add_f32_dpp v72, v72, v72 quad_perm:[2,3,0,1] row_mask:0xf bank_mask:0xf
	v_add_f32_dpp v68, v68, v68 quad_perm:[2,3,0,1] row_mask:0xf bank_mask:0xf
	v_add_f32_dpp v60, v60, v60 quad_perm:[2,3,0,1] row_mask:0xf bank_mask:0xf
	v_add_f32_dpp v52, v52, v52 quad_perm:[2,3,0,1] row_mask:0xf bank_mask:0xf
	v_add_f32_dpp v48, v48, v48 quad_perm:[2,3,0,1] row_mask:0xf bank_mask:0xf
	v_add_f32_dpp v40, v40, v40 quad_perm:[2,3,0,1] row_mask:0xf bank_mask:0xf
	v_add_f32_dpp v36, v36, v36 quad_perm:[2,3,0,1] row_mask:0xf bank_mask:0xf
	v_add_f32_dpp v28, v28, v28 quad_perm:[2,3,0,1] row_mask:0xf bank_mask:0xf
	v_add_f32_dpp v24, v24, v24 quad_perm:[2,3,0,1] row_mask:0xf bank_mask:0xf
	v_add_f32_dpp v20, v20, v20 quad_perm:[2,3,0,1] row_mask:0xf bank_mask:0xf
	v_add_f32_dpp v16, v16, v16 quad_perm:[2,3,0,1] row_mask:0xf bank_mask:0xf
	v_add_f32_dpp v12, v12, v12 quad_perm:[2,3,0,1] row_mask:0xf bank_mask:0xf
	v_add_f32_dpp v8, v8, v8 quad_perm:[2,3,0,1] row_mask:0xf bank_mask:0xf
	v_add_f32_dpp v4, v4, v4 quad_perm:[2,3,0,1] row_mask:0xf bank_mask:0xf
	v_add_f32_dpp v80, v80, v80 row_half_mirror row_mask:0xf bank_mask:0xf
	v_add_f32_dpp v76, v76, v76 row_half_mirror row_mask:0xf bank_mask:0xf
	v_add_f32_dpp v72, v72, v72 row_half_mirror row_mask:0xf bank_mask:0xf
	v_add_f32_dpp v68, v68, v68 row_half_mirror row_mask:0xf bank_mask:0xf
	v_add_f32_dpp v60, v60, v60 row_half_mirror row_mask:0xf bank_mask:0xf
	v_add_f32_dpp v52, v52, v52 row_half_mirror row_mask:0xf bank_mask:0xf
	v_add_f32_dpp v48, v48, v48 row_half_mirror row_mask:0xf bank_mask:0xf
	v_add_f32_dpp v40, v40, v40 row_half_mirror row_mask:0xf bank_mask:0xf
	v_add_f32_dpp v36, v36, v36 row_half_mirror row_mask:0xf bank_mask:0xf
	v_add_f32_dpp v28, v28, v28 row_half_mirror row_mask:0xf bank_mask:0xf
	v_add_f32_dpp v24, v24, v24 row_half_mirror row_mask:0xf bank_mask:0xf
	v_add_f32_dpp v20, v20, v20 row_half_mirror row_mask:0xf bank_mask:0xf
	v_add_f32_dpp v16, v16, v16 row_half_mirror row_mask:0xf bank_mask:0xf
	v_add_f32_dpp v12, v12, v12 row_half_mirror row_mask:0xf bank_mask:0xf
	v_add_f32_dpp v8, v8, v8 row_half_mirror row_mask:0xf bank_mask:0xf
	v_add_f32_dpp v4, v4, v4 row_half_mirror row_mask:0xf bank_mask:0xf
	v_add_f32_dpp v80, v80, v80 row_mirror row_mask:0xf bank_mask:0xf
	v_add_f32_dpp v76, v76, v76 row_mirror row_mask:0xf bank_mask:0xf
	v_add_f32_dpp v72, v72, v72 row_mirror row_mask:0xf bank_mask:0xf
	v_add_f32_dpp v68, v68, v68 row_mirror row_mask:0xf bank_mask:0xf
	v_add_f32_dpp v60, v60, v60 row_mirror row_mask:0xf bank_mask:0xf
	v_add_f32_dpp v52, v52, v52 row_mirror row_mask:0xf bank_mask:0xf
	v_add_f32_dpp v48, v48, v48 row_mirror row_mask:0xf bank_mask:0xf
	v_add_f32_dpp v40, v40, v40 row_mirror row_mask:0xf bank_mask:0xf
	v_add_f32_dpp v36, v36, v36 row_mirror row_mask:0xf bank_mask:0xf
	v_add_f32_dpp v28, v28, v28 row_mirror row_mask:0xf bank_mask:0xf
	v_add_f32_dpp v24, v24, v24 row_mirror row_mask:0xf bank_mask:0xf
	v_add_f32_dpp v20, v20, v20 row_mirror row_mask:0xf bank_mask:0xf
	v_add_f32_dpp v16, v16, v16 row_mirror row_mask:0xf bank_mask:0xf
	v_add_f32_dpp v12, v12, v12 row_mirror row_mask:0xf bank_mask:0xf
	v_add_f32_dpp v8, v8, v8 row_mirror row_mask:0xf bank_mask:0xf
	v_add_f32_dpp v4, v4, v4 row_mirror row_mask:0xf bank_mask:0xf
	ds_bpermute_b32 v81, v144, v80
	ds_bpermute_b32 v77, v144, v76
	ds_bpermute_b32 v73, v144, v72
	ds_bpermute_b32 v69, v144, v68
	ds_bpermute_b32 v61, v144, v60
	ds_bpermute_b32 v53, v144, v52
	ds_bpermute_b32 v49, v144, v48
	ds_bpermute_b32 v41, v144, v40
	ds_bpermute_b32 v37, v144, v36
	ds_bpermute_b32 v29, v144, v28
	ds_bpermute_b32 v25, v144, v24
	ds_bpermute_b32 v21, v144, v20
	ds_bpermute_b32 v17, v144, v16
	ds_bpermute_b32 v13, v144, v12
	ds_bpermute_b32 v9, v144, v8
	ds_bpermute_b32 v5, v144, v4
	s_waitcnt lgkmcnt(0)
	v_add_f32_e32 v80, v80, v81
	v_add_f32_e32 v76, v76, v77
	v_add_f32_e32 v72, v72, v73
	v_add_f32_e32 v68, v68, v69
	v_add_f32_e32 v60, v60, v61
	v_add_f32_e32 v52, v52, v53
	v_add_f32_e32 v48, v48, v49
	v_add_f32_e32 v40, v40, v41
	v_add_f32_e32 v36, v36, v37
	v_add_f32_e32 v28, v28, v29
	v_add_f32_e32 v24, v24, v25
	v_add_f32_e32 v20, v20, v21
	v_add_f32_e32 v16, v16, v17
	v_add_f32_e32 v12, v12, v13
	v_add_f32_e32 v8, v8, v9
	v_add_f32_e32 v4, v4, v5
	s_and_saveexec_b64 s[44:45], s[38:39]
	s_cbranch_execz .Lmy_sc_ab
	ds_write_b32 v139, v80 offset:1024
	ds_write_b32 v139, v76 offset:1032
	ds_write_b32 v139, v72 offset:1040
	ds_write_b32 v139, v68 offset:1048
	ds_write_b32 v139, v60 offset:1056
	ds_write_b32 v139, v52 offset:1064
	ds_write_b32 v139, v48 offset:1072
	ds_write_b32 v139, v40 offset:1080
	ds_write_b32 v139, v36 offset:1088
	ds_write_b32 v139, v28 offset:1096
	ds_write_b32 v139, v24 offset:1104
	ds_write_b32 v139, v20 offset:1112
	ds_write_b32 v139, v16 offset:1120
	ds_write_b32 v139, v12 offset:1128
	ds_write_b32 v139, v8 offset:1136
	ds_write_b32 v139, v4 offset:1144

.LBB0_682:
	s_cmp_eq_u32 s14, s58
	s_mov_b64 s[40:41], -1
	s_cbranch_scc1 .LBB0_756
	v_mov_b32_e32 v132, v204
	v_readlane_b32 s2, v253, 11
	v_and_b32_e32 v133, 31, v132
	v_lshlrev_b32_e32 v2, 3, v133
	global_load_dwordx2 v[142:143], v2, s[50:51]
	global_load_dwordx2 v[134:135], v2, s[66:67]
	v_readlane_b32 s3, v253, 12
	v_bfe_u32 v144, v132, 5, 1
	s_load_dwordx4 s[44:47], s[2:3], 0x10
	v_or_b32_e32 v4, s89, v144
	v_ashrrev_i32_e32 v5, 31, v4
	v_lshlrev_b64 v[80:81], 9, v[4:5]
	v_lshl_add_u64 v[4:5], s[48:49], 0, v[80:81]
	v_lshlrev_b64 v[4:5], 2, v[4:5]
	v_lshlrev_b32_e32 v2, 4, v133
	s_waitcnt lgkmcnt(0)
	v_lshl_add_u64 v[6:7], s[44:45], 0, v[4:5]
	v_lshl_add_u64 v[40:41], s[46:47], 0, v[4:5]
	v_lshl_add_u64 v[4:5], v[6:7], 0, v[2:3]
	s_waitcnt vmcnt(1)
	v_lshlrev_b32_e32 v83, 16, v142
	v_lshlrev_b32_e32 v82, 16, v143
	s_movk_i32 s14, 0x2000
	v_add_co_u32_e32 v6, vcc, s14, v4
	s_movk_i32 s24, 0x4000
	s_nop 0
	v_addc_co_u32_e32 v7, vcc, 0, v5, vcc
	global_load_dwordx4 v[76:79], v[6:7], off offset:-4096 nt
	global_load_dwordx4 v[68:71], v[6:7], off nt
	v_add_co_u32_e32 v6, vcc, s24, v4
	s_movk_i32 s40, 0x6000
	s_nop 0
	v_addc_co_u32_e32 v7, vcc, 0, v5, vcc
	global_load_dwordx4 v[60:63], v[6:7], off offset:-4096 nt
	global_load_dwordx4 v[56:59], v[6:7], off nt
	v_add_co_u32_e32 v6, vcc, s40, v4
	s_mov_b32 s41, 0x8000
	s_nop 0
	v_addc_co_u32_e32 v7, vcc, 0, v5, vcc
	global_load_dwordx4 v[48:51], v[6:7], off offset:-4096 nt
	global_load_dwordx4 v[44:47], v[6:7], off nt
	v_add_co_u32_e32 v6, vcc, s41, v4
	s_mov_b32 s42, 0xa000
	s_nop 0
	v_addc_co_u32_e32 v7, vcc, 0, v5, vcc
	global_load_dwordx4 v[36:39], v[6:7], off offset:-4096 nt
	global_load_dwordx4 v[32:35], v[6:7], off nt
	v_add_co_u32_e32 v6, vcc, s42, v4
	s_mov_b32 s31, 0xe000
	s_nop 0
	v_addc_co_u32_e32 v7, vcc, 0, v5, vcc
	global_load_dwordx4 v[28:31], v[6:7], off offset:-4096 nt
	global_load_dwordx4 v[24:27], v[6:7], off nt
	v_add_co_u32_e32 v6, vcc, s6, v4
	s_mov_b32 s43, 0xf000
	s_nop 0
	v_addc_co_u32_e32 v7, vcc, 0, v5, vcc
	global_load_dwordx4 v[20:23], v[6:7], off offset:-4096 nt
	global_load_dwordx4 v[16:19], v[6:7], off nt
	v_add_co_u32_e32 v6, vcc, s31, v4
	v_lshl_add_u64 v[40:41], v[40:41], 0, v[2:3]
	s_nop 0
	v_addc_co_u32_e32 v7, vcc, 0, v5, vcc
	global_load_dwordx4 v[12:15], v[6:7], off offset:-4096 nt
	global_load_dwordx4 v[8:11], v[6:7], off nt
	v_add_co_u32_e32 v6, vcc, s43, v4
	s_movk_i32 s63, 0x2000
	s_nop 0
	v_addc_co_u32_e32 v7, vcc, 0, v5, vcc
	v_add_co_u32_e32 v42, vcc, s14, v40
	global_load_dwordx4 v[138:141], v[4:5], off nt
	s_nop 0
	global_load_dwordx4 v[4:7], v[6:7], off nt
	v_addc_co_u32_e32 v43, vcc, 0, v41, vcc
	global_load_dwordx4 v[124:127], v[42:43], off offset:-4096 nt
	global_load_dwordx4 v[116:119], v[42:43], off nt
	v_add_co_u32_e32 v42, vcc, s24, v40
	s_movk_i32 s14, 0x4000
	s_nop 0
	v_addc_co_u32_e32 v43, vcc, 0, v41, vcc
	global_load_dwordx4 v[120:123], v[42:43], off offset:-4096 nt
	global_load_dwordx4 v[108:111], v[42:43], off nt
	v_add_co_u32_e32 v42, vcc, s40, v40
	s_movk_i32 s33, 0x6000
	s_nop 0
	v_addc_co_u32_e32 v43, vcc, 0, v41, vcc
	global_load_dwordx4 v[112:115], v[42:43], off offset:-4096 nt
	global_load_dwordx4 v[100:103], v[42:43], off nt
	v_add_co_u32_e32 v42, vcc, s41, v40
	s_mov_b32 s24, 0x8000
	s_nop 0
	v_addc_co_u32_e32 v43, vcc, 0, v41, vcc
	global_load_dwordx4 v[104:107], v[42:43], off offset:-4096 nt
	global_load_dwordx4 v[92:95], v[42:43], off nt
	v_add_co_u32_e32 v42, vcc, s42, v40
	s_mov_b32 s20, 0xa000
	s_nop 0
	v_addc_co_u32_e32 v43, vcc, 0, v41, vcc
	global_load_dwordx4 v[96:99], v[42:43], off offset:-4096 nt
	global_load_dwordx4 v[84:87], v[42:43], off nt
	v_add_co_u32_e32 v42, vcc, s6, v40
	s_mov_b32 s30, 0xe000
	s_nop 0
	v_addc_co_u32_e32 v43, vcc, 0, v41, vcc
	global_load_dwordx4 v[88:91], v[42:43], off offset:-4096 nt
	global_load_dwordx4 v[72:75], v[42:43], off nt
	v_add_co_u32_e32 v42, vcc, s31, v40
	v_and_b32_e32 v137, 0xffff0000, v142
	s_nop 0
	v_addc_co_u32_e32 v43, vcc, 0, v41, vcc
	global_load_dwordx4 v[64:67], v[42:43], off offset:-4096 nt
	global_load_dwordx4 v[52:55], v[42:43], off nt
	v_add_co_u32_e32 v42, vcc, s43, v40
	v_and_b32_e32 v136, 0xffff0000, v143
	s_nop 0
	v_addc_co_u32_e32 v43, vcc, 0, v41, vcc
	global_load_dwordx4 v[128:131], v[40:41], off nt
	s_nop 0
	global_load_dwordx4 v[40:43], v[42:43], off nt
	s_waitcnt vmcnt(17)
	v_mul_f32_e32 v139, v139, v137
	v_fmac_f32_e32 v139, v138, v83
	v_mul_f32_e32 v138, v141, v136
	v_fmac_f32_e32 v138, v140, v82
	v_add_f32_e32 v138, v139, v138
	v_mul_f32_e32 v77, v77, v137
	v_fmac_f32_e32 v77, v76, v83
	v_mul_f32_e32 v76, v79, v136
	v_fmac_f32_e32 v76, v78, v82
	v_add_f32_e32 v76, v77, v76
	v_mul_f32_e32 v69, v69, v137
	v_fmac_f32_e32 v69, v68, v83
	v_mul_f32_e32 v68, v71, v136
	v_fmac_f32_e32 v68, v70, v82
	v_add_f32_e32 v68, v69, v68
	v_mul_f32_e32 v61, v61, v137
	v_fmac_f32_e32 v61, v60, v83
	v_mul_f32_e32 v60, v63, v136
	v_fmac_f32_e32 v60, v62, v82
	v_add_f32_e32 v60, v61, v60
	v_mul_f32_e32 v57, v57, v137
	v_fmac_f32_e32 v57, v56, v83
	v_mul_f32_e32 v56, v59, v136
	v_fmac_f32_e32 v56, v58, v82
	v_add_f32_e32 v56, v57, v56
	v_mul_f32_e32 v49, v49, v137
	v_fmac_f32_e32 v49, v48, v83
	v_mul_f32_e32 v48, v51, v136
	v_fmac_f32_e32 v48, v50, v82
	v_add_f32_e32 v48, v49, v48
	v_mul_f32_e32 v45, v45, v137
	v_fmac_f32_e32 v45, v44, v83
	v_mul_f32_e32 v44, v47, v136
	v_fmac_f32_e32 v44, v46, v82
	v_add_f32_e32 v44, v45, v44
	v_mul_f32_e32 v37, v37, v137
	v_fmac_f32_e32 v37, v36, v83
	v_mul_f32_e32 v36, v39, v136
	v_fmac_f32_e32 v36, v38, v82
	v_add_f32_e32 v36, v37, v36
	v_mul_f32_e32 v33, v33, v137
	v_fmac_f32_e32 v33, v32, v83
	v_mul_f32_e32 v32, v35, v136
	v_fmac_f32_e32 v32, v34, v82
	v_add_f32_e32 v32, v33, v32
	v_mul_f32_e32 v29, v29, v137
	v_fmac_f32_e32 v29, v28, v83
	v_mul_f32_e32 v28, v31, v136
	v_fmac_f32_e32 v28, v30, v82
	v_add_f32_e32 v28, v29, v28
	v_mul_f32_e32 v25, v25, v137
	v_fmac_f32_e32 v25, v24, v83
	v_mul_f32_e32 v24, v27, v136
	v_fmac_f32_e32 v24, v26, v82
	v_add_f32_e32 v24, v25, v24
	v_mul_f32_e32 v21, v21, v137
	v_fmac_f32_e32 v21, v20, v83
	v_mul_f32_e32 v20, v23, v136
	v_fmac_f32_e32 v20, v22, v82
	v_add_f32_e32 v20, v21, v20
	v_mul_f32_e32 v17, v17, v137
	v_fmac_f32_e32 v17, v16, v83
	v_mul_f32_e32 v16, v19, v136
	v_fmac_f32_e32 v16, v18, v82
	v_add_f32_e32 v16, v17, v16
	v_mul_f32_e32 v13, v13, v137
	v_fmac_f32_e32 v13, v12, v83
	v_mul_f32_e32 v12, v15, v136
	v_fmac_f32_e32 v12, v14, v82
	v_add_f32_e32 v12, v13, v12
	v_mul_f32_e32 v9, v9, v137
	v_fmac_f32_e32 v9, v8, v83
	v_mul_f32_e32 v8, v11, v136
	v_fmac_f32_e32 v8, v10, v82
	v_add_f32_e32 v8, v9, v8
	s_waitcnt vmcnt(16)
	v_mul_f32_e32 v5, v5, v137
	v_fmac_f32_e32 v5, v4, v83
	v_mul_f32_e32 v4, v7, v136
	v_fmac_f32_e32 v4, v6, v82
	v_add_f32_e32 v4, v5, v4
	v_cmp_eq_u32_e64 s[40:41], 0, v133
	s_nop 1
	v_add_f32_dpp v138, v138, v138 quad_perm:[1,0,3,2] row_mask:0xf bank_mask:0xf
	v_add_f32_dpp v76, v76, v76 quad_perm:[1,0,3,2] row_mask:0xf bank_mask:0xf
	v_add_f32_dpp v68, v68, v68 quad_perm:[1,0,3,2] row_mask:0xf bank_mask:0xf
	v_add_f32_dpp v60, v60, v60 quad_perm:[1,0,3,2] row_mask:0xf bank_mask:0xf
	v_add_f32_dpp v56, v56, v56 quad_perm:[1,0,3,2] row_mask:0xf bank_mask:0xf
	v_add_f32_dpp v48, v48, v48 quad_perm:[1,0,3,2] row_mask:0xf bank_mask:0xf
	v_add_f32_dpp v44, v44, v44 quad_perm:[1,0,3,2] row_mask:0xf bank_mask:0xf
	v_add_f32_dpp v36, v36, v36 quad_perm:[1,0,3,2] row_mask:0xf bank_mask:0xf
	v_add_f32_dpp v32, v32, v32 quad_perm:[1,0,3,2] row_mask:0xf bank_mask:0xf
	v_add_f32_dpp v28, v28, v28 quad_perm:[1,0,3,2] row_mask:0xf bank_mask:0xf
	v_add_f32_dpp v24, v24, v24 quad_perm:[1,0,3,2] row_mask:0xf bank_mask:0xf
	v_add_f32_dpp v20, v20, v20 quad_perm:[1,0,3,2] row_mask:0xf bank_mask:0xf
	v_add_f32_dpp v16, v16, v16 quad_perm:[1,0,3,2] row_mask:0xf bank_mask:0xf
	v_add_f32_dpp v12, v12, v12 quad_perm:[1,0,3,2] row_mask:0xf bank_mask:0xf
	v_add_f32_dpp v8, v8, v8 quad_perm:[1,0,3,2] row_mask:0xf bank_mask:0xf
	v_add_f32_dpp v4, v4, v4 quad_perm:[1,0,3,2] row_mask:0xf bank_mask:0xf
	v_add_f32_dpp v138, v138, v138 quad_perm:[2,3,0,1] row_mask:0xf bank_mask:0xf
	v_add_f32_dpp v76, v76, v76 quad_perm:[2,3,0,1] row_mask:0xf bank_mask:0xf
	v_add_f32_dpp v68, v68, v68 quad_perm:[2,3,0,1] row_mask:0xf bank_mask:0xf
	v_add_f32_dpp v60, v60, v60 quad_perm:[2,3,0,1] row_mask:0xf bank_mask:0xf
	v_add_f32_dpp v56, v56, v56 quad_perm:[2,3,0,1] row_mask:0xf bank_mask:0xf
	v_add_f32_dpp v48, v48, v48 quad_perm:[2,3,0,1] row_mask:0xf bank_mask:0xf
	v_add_f32_dpp v44, v44, v44 quad_perm:[2,3,0,1] row_mask:0xf bank_mask:0xf
	v_add_f32_dpp v36, v36, v36 quad_perm:[2,3,0,1] row_mask:0xf bank_mask:0xf
	v_add_f32_dpp v32, v32, v32 quad_perm:[2,3,0,1] row_mask:0xf bank_mask:0xf
	v_add_f32_dpp v28, v28, v28 quad_perm:[2,3,0,1] row_mask:0xf bank_mask:0xf
	v_add_f32_dpp v24, v24, v24 quad_perm:[2,3,0,1] row_mask:0xf bank_mask:0xf
	v_add_f32_dpp v20, v20, v20 quad_perm:[2,3,0,1] row_mask:0xf bank_mask:0xf
	v_add_f32_dpp v16, v16, v16 quad_perm:[2,3,0,1] row_mask:0xf bank_mask:0xf
	v_add_f32_dpp v12, v12, v12 quad_perm:[2,3,0,1] row_mask:0xf bank_mask:0xf
	v_add_f32_dpp v8, v8, v8 quad_perm:[2,3,0,1] row_mask:0xf bank_mask:0xf
	v_add_f32_dpp v4, v4, v4 quad_perm:[2,3,0,1] row_mask:0xf bank_mask:0xf
	v_add_f32_dpp v138, v138, v138 row_half_mirror row_mask:0xf bank_mask:0xf
	v_add_f32_dpp v76, v76, v76 row_half_mirror row_mask:0xf bank_mask:0xf
	v_add_f32_dpp v68, v68, v68 row_half_mirror row_mask:0xf bank_mask:0xf
	v_add_f32_dpp v60, v60, v60 row_half_mirror row_mask:0xf bank_mask:0xf
	v_add_f32_dpp v56, v56, v56 row_half_mirror row_mask:0xf bank_mask:0xf
	v_add_f32_dpp v48, v48, v48 row_half_mirror row_mask:0xf bank_mask:0xf
	v_add_f32_dpp v44, v44, v44 row_half_mirror row_mask:0xf bank_mask:0xf
	v_add_f32_dpp v36, v36, v36 row_half_mirror row_mask:0xf bank_mask:0xf
	v_add_f32_dpp v32, v32, v32 row_half_mirror row_mask:0xf bank_mask:0xf
	v_add_f32_dpp v28, v28, v28 row_half_mirror row_mask:0xf bank_mask:0xf
	v_add_f32_dpp v24, v24, v24 row_half_mirror row_mask:0xf bank_mask:0xf
	v_add_f32_dpp v20, v20, v20 row_half_mirror row_mask:0xf bank_mask:0xf
	v_add_f32_dpp v16, v16, v16 row_half_mirror row_mask:0xf bank_mask:0xf
	v_add_f32_dpp v12, v12, v12 row_half_mirror row_mask:0xf bank_mask:0xf
	v_add_f32_dpp v8, v8, v8 row_half_mirror row_mask:0xf bank_mask:0xf
	v_add_f32_dpp v4, v4, v4 row_half_mirror row_mask:0xf bank_mask:0xf
	v_add_f32_dpp v139, v138, v138 row_mirror row_mask:0xf bank_mask:0xf
	v_add_f32_dpp v76, v76, v76 row_mirror row_mask:0xf bank_mask:0xf
	v_add_f32_dpp v68, v68, v68 row_mirror row_mask:0xf bank_mask:0xf
	v_add_f32_dpp v60, v60, v60 row_mirror row_mask:0xf bank_mask:0xf
	v_add_f32_dpp v56, v56, v56 row_mirror row_mask:0xf bank_mask:0xf
	v_add_f32_dpp v48, v48, v48 row_mirror row_mask:0xf bank_mask:0xf
	v_add_f32_dpp v44, v44, v44 row_mirror row_mask:0xf bank_mask:0xf
	v_add_f32_dpp v36, v36, v36 row_mirror row_mask:0xf bank_mask:0xf
	v_add_f32_dpp v32, v32, v32 row_mirror row_mask:0xf bank_mask:0xf
	v_add_f32_dpp v28, v28, v28 row_mirror row_mask:0xf bank_mask:0xf
	v_add_f32_dpp v24, v24, v24 row_mirror row_mask:0xf bank_mask:0xf
	v_add_f32_dpp v20, v20, v20 row_mirror row_mask:0xf bank_mask:0xf
	v_add_f32_dpp v16, v16, v16 row_mirror row_mask:0xf bank_mask:0xf
	v_add_f32_dpp v12, v12, v12 row_mirror row_mask:0xf bank_mask:0xf
	v_add_f32_dpp v8, v8, v8 row_mirror row_mask:0xf bank_mask:0xf
	v_add_f32_dpp v4, v4, v4 row_mirror row_mask:0xf bank_mask:0xf
	ds_bpermute_b32 v140, v209, v139
	ds_bpermute_b32 v77, v209, v76
	ds_bpermute_b32 v69, v209, v68
	ds_bpermute_b32 v61, v209, v60
	ds_bpermute_b32 v57, v209, v56
	ds_bpermute_b32 v49, v209, v48
	ds_bpermute_b32 v45, v209, v44
	ds_bpermute_b32 v37, v209, v36
	ds_bpermute_b32 v33, v209, v32
	ds_bpermute_b32 v29, v209, v28
	ds_bpermute_b32 v25, v209, v24
	ds_bpermute_b32 v21, v209, v20
	ds_bpermute_b32 v17, v209, v16
	ds_bpermute_b32 v13, v209, v12
	ds_bpermute_b32 v9, v209, v8
	ds_bpermute_b32 v5, v209, v4
	s_waitcnt lgkmcnt(0)
	v_add_f32_e32 v139, v139, v140
	v_add_f32_e32 v76, v76, v77
	v_add_f32_e32 v68, v68, v69
	v_add_f32_e32 v60, v60, v61
	v_add_f32_e32 v56, v56, v57
	v_add_f32_e32 v48, v48, v49
	v_add_f32_e32 v44, v44, v45
	v_add_f32_e32 v36, v36, v37
	v_add_f32_e32 v32, v32, v33
	v_add_f32_e32 v28, v28, v29
	v_add_f32_e32 v24, v24, v25
	v_add_f32_e32 v20, v20, v21
	v_add_f32_e32 v16, v16, v17
	v_add_f32_e32 v12, v12, v13
	v_add_f32_e32 v8, v8, v9
	v_add_f32_e32 v4, v4, v5
	v_lshl_add_u32 v138, v144, 2, s90
	s_and_saveexec_b64 s[42:43], s[40:41]
	s_cbranch_execz .Lmy_sc_la
	ds_write_b32 v138, v139
	ds_write_b32 v138, v76 offset:8
	ds_write_b32 v138, v68 offset:16
	ds_write_b32 v138, v60 offset:24
	ds_write_b32 v138, v56 offset:32
	ds_write_b32 v138, v48 offset:40
	ds_write_b32 v138, v44 offset:48
	ds_write_b32 v138, v36 offset:56
	ds_write_b32 v138, v32 offset:64
	ds_write_b32 v138, v28 offset:72
	ds_write_b32 v138, v24 offset:80
	ds_write_b32 v138, v20 offset:88
	ds_write_b32 v138, v16 offset:96
	ds_write_b32 v138, v12 offset:104
	ds_write_b32 v138, v8 offset:112
	ds_write_b32 v138, v4 offset:120

.LBB0_719:
	s_or_b64 exec, exec, s[46:47]
	v_and_b32_e32 v141, 0xffff0000, v134
	v_lshlrev_b32_e32 v137, 16, v134
	v_and_b32_e32 v134, 0xffff0000, v135
	s_waitcnt vmcnt(31)
	v_mul_f32_e32 v81, v81, v141
	v_lshlrev_b32_e32 v136, 16, v135
	v_fmac_f32_e32 v81, v80, v137
	v_mul_f32_e32 v80, v83, v134
	v_fmac_f32_e32 v80, v82, v136
	v_add_f32_e32 v80, v81, v80
	s_waitcnt vmcnt(30)
	v_mul_f32_e32 v77, v77, v141
	v_fmac_f32_e32 v77, v76, v137
	v_mul_f32_e32 v76, v79, v134
	v_fmac_f32_e32 v76, v78, v136
	v_add_f32_e32 v76, v77, v76
	s_waitcnt vmcnt(29)
	v_mul_f32_e32 v69, v69, v141
	v_fmac_f32_e32 v69, v68, v137
	v_mul_f32_e32 v68, v71, v134
	v_fmac_f32_e32 v68, v70, v136
	v_add_f32_e32 v68, v69, v68
	s_waitcnt vmcnt(28)
	v_mul_f32_e32 v61, v61, v141
	v_fmac_f32_e32 v61, v60, v137
	v_mul_f32_e32 v60, v63, v134
	v_fmac_f32_e32 v60, v62, v136
	v_add_f32_e32 v60, v61, v60
	s_waitcnt vmcnt(27)
	v_mul_f32_e32 v57, v57, v141
	v_fmac_f32_e32 v57, v56, v137
	v_mul_f32_e32 v56, v59, v134
	v_fmac_f32_e32 v56, v58, v136
	v_add_f32_e32 v56, v57, v56
	s_waitcnt vmcnt(26)
	v_mul_f32_e32 v49, v49, v141
	v_fmac_f32_e32 v49, v48, v137
	v_mul_f32_e32 v48, v51, v134
	v_fmac_f32_e32 v48, v50, v136
	v_add_f32_e32 v48, v49, v48
	s_waitcnt vmcnt(25)
	v_mul_f32_e32 v45, v45, v141
	v_fmac_f32_e32 v45, v44, v137
	v_mul_f32_e32 v44, v47, v134
	v_fmac_f32_e32 v44, v46, v136
	v_add_f32_e32 v44, v45, v44
	s_waitcnt vmcnt(24)
	v_mul_f32_e32 v37, v37, v141
	v_fmac_f32_e32 v37, v36, v137
	v_mul_f32_e32 v36, v39, v134
	v_fmac_f32_e32 v36, v38, v136
	v_add_f32_e32 v36, v37, v36
	s_waitcnt vmcnt(23)
	v_mul_f32_e32 v33, v33, v141
	v_fmac_f32_e32 v33, v32, v137
	v_mul_f32_e32 v32, v35, v134
	v_fmac_f32_e32 v32, v34, v136
	v_add_f32_e32 v32, v33, v32
	s_waitcnt vmcnt(22)
	v_mul_f32_e32 v29, v29, v141
	v_fmac_f32_e32 v29, v28, v137
	v_mul_f32_e32 v28, v31, v134
	v_fmac_f32_e32 v28, v30, v136
	v_add_f32_e32 v28, v29, v28
	s_waitcnt vmcnt(21)
	v_mul_f32_e32 v25, v25, v141
	v_fmac_f32_e32 v25, v24, v137
	v_mul_f32_e32 v24, v27, v134
	v_fmac_f32_e32 v24, v26, v136
	v_add_f32_e32 v24, v25, v24
	s_waitcnt vmcnt(20)
	v_mul_f32_e32 v21, v21, v141
	v_fmac_f32_e32 v21, v20, v137
	v_mul_f32_e32 v20, v23, v134
	v_fmac_f32_e32 v20, v22, v136
	v_add_f32_e32 v20, v21, v20
	s_waitcnt vmcnt(19)
	v_mul_f32_e32 v17, v17, v141
	v_fmac_f32_e32 v17, v16, v137
	v_mul_f32_e32 v16, v19, v134
	v_fmac_f32_e32 v16, v18, v136
	v_add_f32_e32 v16, v17, v16
	s_waitcnt vmcnt(18)
	v_mul_f32_e32 v13, v13, v141
	v_fmac_f32_e32 v13, v12, v137
	v_mul_f32_e32 v12, v15, v134
	v_fmac_f32_e32 v12, v14, v136
	v_add_f32_e32 v12, v13, v12
	s_waitcnt vmcnt(17)
	v_mul_f32_e32 v9, v9, v141
	v_fmac_f32_e32 v9, v8, v137
	v_mul_f32_e32 v8, v11, v134
	v_fmac_f32_e32 v8, v10, v136
	v_add_f32_e32 v8, v9, v8
	s_waitcnt vmcnt(16)
	v_mul_f32_e32 v5, v5, v141
	v_fmac_f32_e32 v5, v4, v137
	v_mul_f32_e32 v4, v7, v134
	v_fmac_f32_e32 v4, v6, v136
	v_add_f32_e32 v4, v5, v4
	v_add_f32_dpp v80, v80, v80 quad_perm:[1,0,3,2] row_mask:0xf bank_mask:0xf
	v_add_f32_dpp v76, v76, v76 quad_perm:[1,0,3,2] row_mask:0xf bank_mask:0xf
	v_add_f32_dpp v68, v68, v68 quad_perm:[1,0,3,2] row_mask:0xf bank_mask:0xf
	v_add_f32_dpp v60, v60, v60 quad_perm:[1,0,3,2] row_mask:0xf bank_mask:0xf
	v_add_f32_dpp v56, v56, v56 quad_perm:[1,0,3,2] row_mask:0xf bank_mask:0xf
	v_add_f32_dpp v48, v48, v48 quad_perm:[1,0,3,2] row_mask:0xf bank_mask:0xf
	v_add_f32_dpp v44, v44, v44 quad_perm:[1,0,3,2] row_mask:0xf bank_mask:0xf
	v_add_f32_dpp v36, v36, v36 quad_perm:[1,0,3,2] row_mask:0xf bank_mask:0xf
	v_add_f32_dpp v32, v32, v32 quad_perm:[1,0,3,2] row_mask:0xf bank_mask:0xf
	v_add_f32_dpp v28, v28, v28 quad_perm:[1,0,3,2] row_mask:0xf bank_mask:0xf
	v_add_f32_dpp v24, v24, v24 quad_perm:[1,0,3,2] row_mask:0xf bank_mask:0xf
	v_add_f32_dpp v20, v20, v20 quad_perm:[1,0,3,2] row_mask:0xf bank_mask:0xf
	v_add_f32_dpp v16, v16, v16 quad_perm:[1,0,3,2] row_mask:0xf bank_mask:0xf
	v_add_f32_dpp v12, v12, v12 quad_perm:[1,0,3,2] row_mask:0xf bank_mask:0xf
	v_add_f32_dpp v8, v8, v8 quad_perm:[1,0,3,2] row_mask:0xf bank_mask:0xf
	v_add_f32_dpp v4, v4, v4 quad_perm:[1,0,3,2] row_mask:0xf bank_mask:0xf
	v_add_f32_dpp v80, v80, v80 quad_perm:[2,3,0,1] row_mask:0xf bank_mask:0xf
	v_add_f32_dpp v76, v76, v76 quad_perm:[2,3,0,1] row_mask:0xf bank_mask:0xf
	v_add_f32_dpp v68, v68, v68 quad_perm:[2,3,0,1] row_mask:0xf bank_mask:0xf
	v_add_f32_dpp v60, v60, v60 quad_perm:[2,3,0,1] row_mask:0xf bank_mask:0xf
	v_add_f32_dpp v56, v56, v56 quad_perm:[2,3,0,1] row_mask:0xf bank_mask:0xf
	v_add_f32_dpp v48, v48, v48 quad_perm:[2,3,0,1] row_mask:0xf bank_mask:0xf
	v_add_f32_dpp v44, v44, v44 quad_perm:[2,3,0,1] row_mask:0xf bank_mask:0xf
	v_add_f32_dpp v36, v36, v36 quad_perm:[2,3,0,1] row_mask:0xf bank_mask:0xf
	v_add_f32_dpp v32, v32, v32 quad_perm:[2,3,0,1] row_mask:0xf bank_mask:0xf
	v_add_f32_dpp v28, v28, v28 quad_perm:[2,3,0,1] row_mask:0xf bank_mask:0xf
	v_add_f32_dpp v24, v24, v24 quad_perm:[2,3,0,1] row_mask:0xf bank_mask:0xf
	v_add_f32_dpp v20, v20, v20 quad_perm:[2,3,0,1] row_mask:0xf bank_mask:0xf
	v_add_f32_dpp v16, v16, v16 quad_perm:[2,3,0,1] row_mask:0xf bank_mask:0xf
	v_add_f32_dpp v12, v12, v12 quad_perm:[2,3,0,1] row_mask:0xf bank_mask:0xf
	v_add_f32_dpp v8, v8, v8 quad_perm:[2,3,0,1] row_mask:0xf bank_mask:0xf
	v_add_f32_dpp v4, v4, v4 quad_perm:[2,3,0,1] row_mask:0xf bank_mask:0xf
	v_add_f32_dpp v80, v80, v80 row_half_mirror row_mask:0xf bank_mask:0xf
	v_add_f32_dpp v76, v76, v76 row_half_mirror row_mask:0xf bank_mask:0xf
	v_add_f32_dpp v68, v68, v68 row_half_mirror row_mask:0xf bank_mask:0xf
	v_add_f32_dpp v60, v60, v60 row_half_mirror row_mask:0xf bank_mask:0xf
	v_add_f32_dpp v56, v56, v56 row_half_mirror row_mask:0xf bank_mask:0xf
	v_add_f32_dpp v48, v48, v48 row_half_mirror row_mask:0xf bank_mask:0xf
	v_add_f32_dpp v44, v44, v44 row_half_mirror row_mask:0xf bank_mask:0xf
	v_add_f32_dpp v36, v36, v36 row_half_mirror row_mask:0xf bank_mask:0xf
	v_add_f32_dpp v32, v32, v32 row_half_mirror row_mask:0xf bank_mask:0xf
	v_add_f32_dpp v28, v28, v28 row_half_mirror row_mask:0xf bank_mask:0xf
	v_add_f32_dpp v24, v24, v24 row_half_mirror row_mask:0xf bank_mask:0xf
	v_add_f32_dpp v20, v20, v20 row_half_mirror row_mask:0xf bank_mask:0xf
	v_add_f32_dpp v16, v16, v16 row_half_mirror row_mask:0xf bank_mask:0xf
	v_add_f32_dpp v12, v12, v12 row_half_mirror row_mask:0xf bank_mask:0xf
	v_add_f32_dpp v8, v8, v8 row_half_mirror row_mask:0xf bank_mask:0xf
	v_add_f32_dpp v4, v4, v4 row_half_mirror row_mask:0xf bank_mask:0xf
	v_add_f32_dpp v80, v80, v80 row_mirror row_mask:0xf bank_mask:0xf
	v_add_f32_dpp v76, v76, v76 row_mirror row_mask:0xf bank_mask:0xf
	v_add_f32_dpp v68, v68, v68 row_mirror row_mask:0xf bank_mask:0xf
	v_add_f32_dpp v60, v60, v60 row_mirror row_mask:0xf bank_mask:0xf
	v_add_f32_dpp v56, v56, v56 row_mirror row_mask:0xf bank_mask:0xf
	v_add_f32_dpp v48, v48, v48 row_mirror row_mask:0xf bank_mask:0xf
	v_add_f32_dpp v44, v44, v44 row_mirror row_mask:0xf bank_mask:0xf
	v_add_f32_dpp v36, v36, v36 row_mirror row_mask:0xf bank_mask:0xf
	v_add_f32_dpp v32, v32, v32 row_mirror row_mask:0xf bank_mask:0xf
	v_add_f32_dpp v28, v28, v28 row_mirror row_mask:0xf bank_mask:0xf
	v_add_f32_dpp v24, v24, v24 row_mirror row_mask:0xf bank_mask:0xf
	v_add_f32_dpp v20, v20, v20 row_mirror row_mask:0xf bank_mask:0xf
	v_add_f32_dpp v16, v16, v16 row_mirror row_mask:0xf bank_mask:0xf
	v_add_f32_dpp v12, v12, v12 row_mirror row_mask:0xf bank_mask:0xf
	v_add_f32_dpp v8, v8, v8 row_mirror row_mask:0xf bank_mask:0xf
	v_add_f32_dpp v4, v4, v4 row_mirror row_mask:0xf bank_mask:0xf
	ds_bpermute_b32 v81, v209, v80
	ds_bpermute_b32 v77, v209, v76
	ds_bpermute_b32 v69, v209, v68
	ds_bpermute_b32 v61, v209, v60
	ds_bpermute_b32 v57, v209, v56
	ds_bpermute_b32 v49, v209, v48
	ds_bpermute_b32 v45, v209, v44
	ds_bpermute_b32 v37, v209, v36
	ds_bpermute_b32 v33, v209, v32
	ds_bpermute_b32 v29, v209, v28
	ds_bpermute_b32 v25, v209, v24
	ds_bpermute_b32 v21, v209, v20
	ds_bpermute_b32 v17, v209, v16
	ds_bpermute_b32 v13, v209, v12
	ds_bpermute_b32 v9, v209, v8
	ds_bpermute_b32 v5, v209, v4
	s_waitcnt lgkmcnt(0)
	v_add_f32_e32 v80, v80, v81
	v_add_f32_e32 v76, v76, v77
	v_add_f32_e32 v68, v68, v69
	v_add_f32_e32 v60, v60, v61
	v_add_f32_e32 v56, v56, v57
	v_add_f32_e32 v48, v48, v49
	v_add_f32_e32 v44, v44, v45
	v_add_f32_e32 v36, v36, v37
	v_add_f32_e32 v32, v32, v33
	v_add_f32_e32 v28, v28, v29
	v_add_f32_e32 v24, v24, v25
	v_add_f32_e32 v20, v20, v21
	v_add_f32_e32 v16, v16, v17
	v_add_f32_e32 v12, v12, v13
	v_add_f32_e32 v8, v8, v9
	v_add_f32_e32 v4, v4, v5
	s_and_saveexec_b64 s[46:47], s[40:41]
	s_cbranch_execz .Lmy_sc_lb
	ds_write_b32 v138, v80 offset:1024
	ds_write_b32 v138, v76 offset:1032
	ds_write_b32 v138, v68 offset:1040
	ds_write_b32 v138, v60 offset:1048
	ds_write_b32 v138, v56 offset:1056
	ds_write_b32 v138, v48 offset:1064
	ds_write_b32 v138, v44 offset:1072
	ds_write_b32 v138, v36 offset:1080
	ds_write_b32 v138, v32 offset:1088
	ds_write_b32 v138, v28 offset:1096
	ds_write_b32 v138, v24 offset:1104
	ds_write_b32 v138, v20 offset:1112
	ds_write_b32 v138, v16 offset:1120
	ds_write_b32 v138, v12 offset:1128
	ds_write_b32 v138, v8 offset:1136
	ds_write_b32 v138, v4 offset:1144
